# seam P12->P13 (counters instead of the grid barrier, rebalanced last row phase), unused XCC-id read dropped
# speedup vs baseline: 1.0179x; 1.0008x over previous
; __device__ __forceinline__ int fresh_tid(int wv) { int l; asm volatile("v_mbcnt_lo_u32_b32 %0, -1, 0\n\tv_mbcnt_hi_u32_b32 %0, -1, %0" : "=v"(l)); return wv * 64 + l; }
; #define LAS __attribute__((address_space(3)))
; __device__ __forceinline__ unsigned xb_add(unsigned* p, unsigned v) { return __hip_atomic_fetch_add(p, v, __ATOMIC_RELAXED, __HIP_MEMORY_SCOPE_AGENT); }
; __device__ __forceinline__ unsigned xb_xcc_id() { return (unsigned)__builtin_amdgcn_s_getreg((3 << 11) | 20) & 0xFu; }
; #define GSYNC() do { for (int r_ = 0; r_ < REP_SYNC; ++r_) xcd_barrier((unsigned*)ws, (volatile LAS unsigned*)(lds + LDS_BYTES - 16), wv); FRESH(); } while (0)
; __device__ __forceinline__ void xcd_barrier(unsigned* barw, volatile LAS unsigned* stw, const int wv) {
;     XcdBarrier b; b.bar = barw; b.x = xb_xcc_id(); b.st = stw;
;     asm volatile("s_waitcnt vmcnt(0)" ::: "memory");
;     __syncthreads();
;     if (fresh_tid(wv) == 0) {
;         unsigned* bar = b.bar;
;         __builtin_amdgcn_s_waitcnt(0);
;         unsigned nloc = b.st[0], nx = b.st[1];
;         if (nloc == 0u) { xcd_barrier_complete(bar, b.x, nloc, nx); b.st[0] = nloc; b.st[1] = nx; }
;         const unsigned old = xb_add(&bar[XB_XSUB(b.x)], 1u);
; __global__ void __launch_bounds__(512, 2) hymba_mega(Params P_unused) {
;     ...
;     GSYNC();
.LBB0_1083:
	s_waitcnt vmcnt(0)
	s_waitcnt vmcnt(0) lgkmcnt(0)
	s_barrier
	v_mbcnt_lo_u32_b32 v0, -1, 0
	v_mbcnt_hi_u32_b32 v0, -1, v0
	s_nop 0
	v_cmp_eq_u32_e32 vcc, s74, v0
	s_and_saveexec_b64 s[0:1], vcc
	s_cbranch_execz .LBB0_1135
	s_cmp_lt_u32 s73, 0x200
	s_cbranch_scc0 .Lseam_nosplit
	buffer_wbl2 sc1
	s_waitcnt vmcnt(0)
	v_mov_b32_e32 v0, 0x3900
	v_mov_b32_e32 v1, 1
	global_atomic_add v0, v1, s[2:3]
